# v072 + the first QK MFMA of each attention step is issued at the very top of the step, ahead of the scalar address math, prefetch loads and exp pre-fill
# speedup vs baseline: 1.0025x; 1.0025x over previous
.Lattn_fx_top:
	s_waitcnt lgkmcnt(0)
	v_mfma_f32_32x32x16_bf16 v[114:129], v[162:165], v[130:133], v[50:65]
	s_add_i32 s11, s10, -1
	s_min_i32 s1, s11, s58
	s_mul_i32 s44, s1, 0xa0000
	s_add_u32 s44, s3, s44
	s_addc_u32 s45, s12, 0
	s_lshl_b32 s46, s1, 7
	s_add_u32 s46, s15, s46
	s_addc_u32 s47, s23, 0
	s_add_i32 s24, s10, -2
	s_cmp_lt_u32 s24, s16
	s_cselect_b64 s[0:1], -1, 0
	global_load_dwordx4 v[154:157], v252, s[44:45] offset:1024
	global_load_dwordx4 v[158:161], v253, s[46:47]
	v_exp_f32_e32 v66, v66
	v_exp_f32_e32 v67, v67
	v_exp_f32_e32 v68, v68
	v_exp_f32_e32 v69, v69
	v_add_f32_e32 v246, v66, v67
	v_cvt_pk_bf16_f32 v66, v66, v67
	ds_read_b128 v[86:89], v248 offset:36864
	ds_read_b128 v[216:219], v248 offset:41472
	v_exp_f32_e32 v70, v70
	v_exp_f32_e32 v71, v71
	v_add_f32_e32 v246, v68, v246
	v_add_f32_e32 v246, v69, v246
	v_cvt_pk_bf16_f32 v67, v68, v69
	v_mfma_f32_32x32x16_bf16 v[98:113], v[178:181], v[130:133], v[50:65]
	ds_read_b128 v[90:93], v248 offset:36896
	ds_read_b128 v[220:223], v248 offset:41504
	v_exp_f32_e32 v72, v72
	v_exp_f32_e32 v73, v73
	v_add_f32_e32 v246, v70, v246
	v_add_f32_e32 v246, v71, v246
	v_cvt_pk_bf16_f32 v68, v70, v71
	v_mfma_f32_32x32x16_bf16 v[114:129], v[166:169], v[134:137], v[114:129]
	ds_read_b128 v[94:97], v248 offset:36928
	ds_read_b128 v[224:227], v248 offset:41536
	v_exp_f32_e32 v74, v74
	v_exp_f32_e32 v75, v75
	v_add_f32_e32 v246, v72, v246
	v_add_f32_e32 v246, v73, v246
	v_cvt_pk_bf16_f32 v69, v72, v73
	v_mfma_f32_32x32x16_bf16 v[98:113], v[182:185], v[134:137], v[98:113]
	ds_read_b128 v[212:215], v248 offset:36960
	ds_read_b128 v[242:245], v248 offset:41568
	v_exp_f32_e32 v76, v76
	v_exp_f32_e32 v77, v77
	v_add_f32_e32 v246, v74, v246
	v_add_f32_e32 v246, v75, v246
	v_cvt_pk_bf16_f32 v70, v74, v75
	v_mfma_f32_32x32x16_bf16 v[114:129], v[170:173], v[138:141], v[114:129]
	s_cmp_ge_u32 s24, s16
	s_cbranch_scc1 .Lattn_fx_skipw1
	s_waitcnt vmcnt(2)
	ds_write_b128 v192, v[146:149] offset:18432
	ds_write_b128 v204, v[150:153] offset:27648
.Lattn_fx_skipw1:
	v_exp_f32_e32 v78, v78
	v_exp_f32_e32 v79, v79
	v_add_f32_e32 v246, v76, v246
	v_add_f32_e32 v246, v77, v246
	v_cvt_pk_bf16_f32 v71, v76, v77
	v_mfma_f32_32x32x16_bf16 v[98:113], v[186:189], v[138:141], v[98:113]
	v_exp_f32_e32 v80, v80
	v_exp_f32_e32 v81, v81
	v_add_f32_e32 v246, v78, v246
	v_add_f32_e32 v246, v79, v246
	v_cvt_pk_bf16_f32 v72, v78, v79
	v_mfma_f32_32x32x16_bf16 v[114:129], v[174:177], v[142:145], v[114:129]
	v_exp_f32_e32 v34, v34
	v_exp_f32_e32 v35, v35
	v_add_f32_e32 v246, v80, v246
	v_add_f32_e32 v246, v81, v246
	v_cvt_pk_bf16_f32 v73, v80, v81
	v_mfma_f32_32x32x16_bf16 v[98:113], v[82:85], v[142:145], v[98:113]
	v_exp_f32_e32 v36, v36
	v_exp_f32_e32 v37, v37
	v_add_f32_e32 v247, v34, v35
	v_cvt_pk_bf16_f32 v74, v34, v35
	s_waitcnt lgkmcnt(0)
	v_mfma_f32_32x32x16_bf16 v[18:33], v[86:89], v[66:69], v[18:33]
	s_barrier
	ds_read_b128 v[162:165], v193 offset:18432
	ds_read_b128 v[178:181], v193 offset:23040
	v_exp_f32_e32 v38, v38
	v_exp_f32_e32 v39, v39
	v_add_f32_e32 v247, v36, v247
	v_add_f32_e32 v247, v37, v247
	v_cvt_pk_bf16_f32 v75, v36, v37
	v_mfma_f32_32x32x16_bf16 v[2:17], v[216:219], v[66:69], v[2:17]
	ds_read_b128 v[166:169], v193 offset:18464
	ds_read_b128 v[182:185], v193 offset:23072
	v_exp_f32_e32 v40, v40
	v_exp_f32_e32 v41, v41
	v_add_f32_e32 v247, v38, v247
	v_add_f32_e32 v247, v39, v247
	v_cvt_pk_bf16_f32 v76, v38, v39
	v_mfma_f32_32x32x16_bf16 v[18:33], v[90:93], v[70:73], v[18:33]
	ds_read_b128 v[170:173], v193 offset:18496
	ds_read_b128 v[186:189], v193 offset:23104
	v_exp_f32_e32 v42, v42
	v_exp_f32_e32 v43, v43
	v_add_f32_e32 v247, v40, v247
	v_add_f32_e32 v247, v41, v247
	v_cvt_pk_bf16_f32 v77, v40, v41
	v_mfma_f32_32x32x16_bf16 v[2:17], v[220:223], v[70:73], v[2:17]
	ds_read_b128 v[174:177], v193 offset:18528
	ds_read_b128 v[82:85], v193 offset:23136
	v_exp_f32_e32 v44, v44
	v_exp_f32_e32 v45, v45
	v_add_f32_e32 v247, v42, v247
	v_add_f32_e32 v247, v43, v247
	v_cvt_pk_bf16_f32 v78, v42, v43
	v_mfma_f32_32x32x16_bf16 v[18:33], v[94:97], v[74:77], v[18:33]
	v_exp_f32_e32 v46, v46
	v_exp_f32_e32 v47, v47
	v_add_f32_e32 v247, v44, v247
	v_add_f32_e32 v247, v45, v247
	v_cvt_pk_bf16_f32 v79, v44, v45
	v_mfma_f32_32x32x16_bf16 v[2:17], v[224:227], v[74:77], v[2:17]
	v_exp_f32_e32 v48, v48
	v_exp_f32_e32 v49, v49
	v_add_f32_e32 v247, v46, v247
	v_add_f32_e32 v247, v47, v247
	v_cvt_pk_bf16_f32 v80, v46, v47
	v_cvt_pk_bf16_f32 v81, v48, v49
	v_add_f32_e32 v247, v48, v247
	v_add_f32_e32 v247, v49, v247
	v_mfma_f32_32x32x16_bf16 v[18:33], v[212:215], v[78:81], v[18:33]
	v_mfma_f32_32x32x16_bf16 v[2:17], v[242:245], v[78:81], v[2:17]
	v_add_f32_e32 v210, v210, v246
	v_add_f32_e32 v210, v210, v247
	s_waitcnt lgkmcnt(0)
	v_mfma_f32_32x32x16_bf16 v[66:81], v[162:165], v[130:133], v[50:65]
	s_min_i32 s24, s10, s58
	s_mul_i32 s44, s24, 0xa0000
	s_add_u32 s44, s3, s44
	s_addc_u32 s45, s12, 0
	s_lshl_b32 s46, s24, 7
	s_add_u32 s46, s15, s46
	s_addc_u32 s47, s23, 0
	global_load_dwordx4 v[146:149], v252, s[44:45] offset:1024
	global_load_dwordx4 v[150:153], v253, s[46:47]
	v_exp_f32_e32 v114, v114
	v_exp_f32_e32 v115, v115
	v_exp_f32_e32 v116, v116
	v_exp_f32_e32 v117, v117
	v_add_f32_e32 v246, v114, v115
	v_cvt_pk_bf16_f32 v114, v114, v115
	ds_read_b128 v[86:89], v248
	ds_read_b128 v[216:219], v248 offset:4608
	v_exp_f32_e32 v118, v118
	v_exp_f32_e32 v119, v119
	v_add_f32_e32 v246, v116, v246
	v_add_f32_e32 v246, v117, v246
	v_cvt_pk_bf16_f32 v115, v116, v117
	v_mfma_f32_32x32x16_bf16 v[34:49], v[178:181], v[130:133], v[50:65]
	ds_read_b128 v[90:93], v248 offset:32
	ds_read_b128 v[220:223], v248 offset:4640
	v_exp_f32_e32 v120, v120
	v_exp_f32_e32 v121, v121
	v_add_f32_e32 v246, v118, v246
	v_add_f32_e32 v246, v119, v246
	v_cvt_pk_bf16_f32 v116, v118, v119
	v_mfma_f32_32x32x16_bf16 v[66:81], v[166:169], v[134:137], v[66:81]
	ds_read_b128 v[94:97], v248 offset:64
	ds_read_b128 v[224:227], v248 offset:4672
	v_exp_f32_e32 v122, v122
	v_exp_f32_e32 v123, v123
	v_add_f32_e32 v246, v120, v246
	v_add_f32_e32 v246, v121, v246
	v_cvt_pk_bf16_f32 v117, v120, v121
	v_mfma_f32_32x32x16_bf16 v[34:49], v[182:185], v[134:137], v[34:49]
	ds_read_b128 v[212:215], v248 offset:96
	ds_read_b128 v[242:245], v248 offset:4704
	v_exp_f32_e32 v124, v124
	v_exp_f32_e32 v125, v125
	v_add_f32_e32 v246, v122, v246
	v_add_f32_e32 v246, v123, v246
	v_cvt_pk_bf16_f32 v118, v122, v123
	v_mfma_f32_32x32x16_bf16 v[66:81], v[170:173], v[138:141], v[66:81]
	s_cmp_ge_u32 s11, s16
	s_cbranch_scc1 .Lattn_fx_skipw2
	s_waitcnt vmcnt(2)
	ds_write_b128 v192, v[154:157] offset:55296
	ds_write_b128 v204, v[158:161] offset:64512
.Lattn_fx_skipw2:
	v_exp_f32_e32 v126, v126
	v_exp_f32_e32 v127, v127
	v_add_f32_e32 v246, v124, v246
	v_add_f32_e32 v246, v125, v246
	v_cvt_pk_bf16_f32 v119, v124, v125
	v_mfma_f32_32x32x16_bf16 v[34:49], v[186:189], v[138:141], v[34:49]
	v_exp_f32_e32 v128, v128
	v_exp_f32_e32 v129, v129
	v_add_f32_e32 v246, v126, v246
	v_add_f32_e32 v246, v127, v246
	v_cvt_pk_bf16_f32 v120, v126, v127
	v_mfma_f32_32x32x16_bf16 v[66:81], v[174:177], v[142:145], v[66:81]
	v_exp_f32_e32 v98, v98
	v_exp_f32_e32 v99, v99
	v_add_f32_e32 v246, v128, v246
	v_add_f32_e32 v246, v129, v246
	v_cvt_pk_bf16_f32 v121, v128, v129
	v_mfma_f32_32x32x16_bf16 v[34:49], v[82:85], v[142:145], v[34:49]
	v_exp_f32_e32 v100, v100
	v_exp_f32_e32 v101, v101
	v_add_f32_e32 v247, v98, v99
	v_cvt_pk_bf16_f32 v122, v98, v99
	s_waitcnt lgkmcnt(0)
	v_mfma_f32_32x32x16_bf16 v[18:33], v[86:89], v[114:117], v[18:33]
	s_barrier
	ds_read_b128 v[162:165], v193 offset:55296
	ds_read_b128 v[178:181], v193 offset:59904
	v_exp_f32_e32 v102, v102
	v_exp_f32_e32 v103, v103
	v_add_f32_e32 v247, v100, v247
	v_add_f32_e32 v247, v101, v247
	v_cvt_pk_bf16_f32 v123, v100, v101
	v_mfma_f32_32x32x16_bf16 v[2:17], v[216:219], v[114:117], v[2:17]
	ds_read_b128 v[166:169], v193 offset:55328
	ds_read_b128 v[182:185], v193 offset:59936
	v_exp_f32_e32 v104, v104
	v_exp_f32_e32 v105, v105
	v_add_f32_e32 v247, v102, v247
	v_add_f32_e32 v247, v103, v247
	v_cvt_pk_bf16_f32 v124, v102, v103
	v_mfma_f32_32x32x16_bf16 v[18:33], v[90:93], v[118:121], v[18:33]
	ds_read_b128 v[170:173], v193 offset:55360
	ds_read_b128 v[186:189], v193 offset:59968
	v_exp_f32_e32 v106, v106
	v_exp_f32_e32 v107, v107
	v_add_f32_e32 v247, v104, v247
	v_add_f32_e32 v247, v105, v247
	v_cvt_pk_bf16_f32 v125, v104, v105
	v_mfma_f32_32x32x16_bf16 v[2:17], v[220:223], v[118:121], v[2:17]
	ds_read_b128 v[174:177], v193 offset:55392
	ds_read_b128 v[82:85], v193 offset:60000
	v_exp_f32_e32 v108, v108
	v_exp_f32_e32 v109, v109
	v_add_f32_e32 v247, v106, v247
	v_add_f32_e32 v247, v107, v247
	v_cvt_pk_bf16_f32 v126, v106, v107
	v_mfma_f32_32x32x16_bf16 v[18:33], v[94:97], v[122:125], v[18:33]
	v_exp_f32_e32 v110, v110
	v_exp_f32_e32 v111, v111
	v_add_f32_e32 v247, v108, v247
	v_add_f32_e32 v247, v109, v247
	v_cvt_pk_bf16_f32 v127, v108, v109
	v_mfma_f32_32x32x16_bf16 v[2:17], v[224:227], v[122:125], v[2:17]
	v_exp_f32_e32 v112, v112
	v_exp_f32_e32 v113, v113
	v_add_f32_e32 v247, v110, v247
	v_add_f32_e32 v247, v111, v247
	v_cvt_pk_bf16_f32 v128, v110, v111
	v_cvt_pk_bf16_f32 v129, v112, v113
	v_add_f32_e32 v247, v112, v247
	v_add_f32_e32 v247, v113, v247
	v_mfma_f32_32x32x16_bf16 v[18:33], v[212:215], v[126:129], v[18:33]
	v_mfma_f32_32x32x16_bf16 v[2:17], v[242:245], v[126:129], v[2:17]
	v_add_f32_e32 v210, v210, v246
	v_add_f32_e32 v210, v210, v247
	s_add_i32 s10, s10, 2
	s_cmp_lt_u32 s11, s16
	s_cbranch_scc0 .Lattn_fx_exit0
	s_waitcnt lgkmcnt(0)
	v_mfma_f32_32x32x16_bf16 v[114:129], v[162:165], v[130:133], v[50:65]
	s_add_i32 s11, s10, -1
	s_min_i32 s1, s11, s58
	s_mul_i32 s44, s1, 0xa0000
	s_add_u32 s44, s3, s44
	s_addc_u32 s45, s12, 0
	s_lshl_b32 s46, s1, 7
	s_add_u32 s46, s15, s46
	s_addc_u32 s47, s23, 0
	s_add_i32 s24, s10, -2
	s_cmp_lt_u32 s24, s16
	s_cselect_b64 s[0:1], -1, 0
	global_load_dwordx4 v[154:157], v252, s[44:45] offset:1024
	global_load_dwordx4 v[158:161], v253, s[46:47]
	v_exp_f32_e32 v66, v66
	v_exp_f32_e32 v67, v67
	v_exp_f32_e32 v68, v68
	v_exp_f32_e32 v69, v69
	v_add_f32_e32 v246, v66, v67
	v_cvt_pk_bf16_f32 v66, v66, v67
	ds_read_b128 v[86:89], v248 offset:18432
	ds_read_b128 v[216:219], v248 offset:23040
	v_exp_f32_e32 v70, v70
	v_exp_f32_e32 v71, v71
	v_add_f32_e32 v246, v68, v246
	v_add_f32_e32 v246, v69, v246
	v_cvt_pk_bf16_f32 v67, v68, v69
	v_mfma_f32_32x32x16_bf16 v[98:113], v[178:181], v[130:133], v[50:65]
	ds_read_b128 v[90:93], v248 offset:18464
	ds_read_b128 v[220:223], v248 offset:23072
	v_exp_f32_e32 v72, v72
	v_exp_f32_e32 v73, v73
	v_add_f32_e32 v246, v70, v246
	v_add_f32_e32 v246, v71, v246
	v_cvt_pk_bf16_f32 v68, v70, v71
	v_mfma_f32_32x32x16_bf16 v[114:129], v[166:169], v[134:137], v[114:129]
	ds_read_b128 v[94:97], v248 offset:18496
	ds_read_b128 v[224:227], v248 offset:23104
	v_exp_f32_e32 v74, v74
	v_exp_f32_e32 v75, v75
	v_add_f32_e32 v246, v72, v246
	v_add_f32_e32 v246, v73, v246
	v_cvt_pk_bf16_f32 v69, v72, v73
	v_mfma_f32_32x32x16_bf16 v[98:113], v[182:185], v[134:137], v[98:113]
	ds_read_b128 v[212:215], v248 offset:18528
	ds_read_b128 v[242:245], v248 offset:23136
	v_exp_f32_e32 v76, v76
	v_exp_f32_e32 v77, v77
	v_add_f32_e32 v246, v74, v246
	v_add_f32_e32 v246, v75, v246
	v_cvt_pk_bf16_f32 v70, v74, v75
	v_mfma_f32_32x32x16_bf16 v[114:129], v[170:173], v[138:141], v[114:129]
	s_cmp_ge_u32 s24, s16
	s_cbranch_scc1 .Lattn_fx_skipw3
	s_waitcnt vmcnt(2)
	ds_write_b128 v192, v[146:149] offset:36864
	ds_write_b128 v204, v[150:153] offset:46080
.Lattn_fx_skipw3:
	v_exp_f32_e32 v78, v78
	v_exp_f32_e32 v79, v79
	v_add_f32_e32 v246, v76, v246
	v_add_f32_e32 v246, v77, v246
	v_cvt_pk_bf16_f32 v71, v76, v77
	v_mfma_f32_32x32x16_bf16 v[98:113], v[186:189], v[138:141], v[98:113]
	v_exp_f32_e32 v80, v80
	v_exp_f32_e32 v81, v81
	v_add_f32_e32 v246, v78, v246
	v_add_f32_e32 v246, v79, v246
	v_cvt_pk_bf16_f32 v72, v78, v79
	v_mfma_f32_32x32x16_bf16 v[114:129], v[174:177], v[142:145], v[114:129]
	v_exp_f32_e32 v34, v34
	v_exp_f32_e32 v35, v35
	v_add_f32_e32 v246, v80, v246
	v_add_f32_e32 v246, v81, v246
	v_cvt_pk_bf16_f32 v73, v80, v81
	v_mfma_f32_32x32x16_bf16 v[98:113], v[82:85], v[142:145], v[98:113]
	v_exp_f32_e32 v36, v36
	v_exp_f32_e32 v37, v37
	v_add_f32_e32 v247, v34, v35
	v_cvt_pk_bf16_f32 v74, v34, v35
	s_waitcnt lgkmcnt(0)
	v_mfma_f32_32x32x16_bf16 v[18:33], v[86:89], v[66:69], v[18:33]
	s_barrier
	ds_read_b128 v[162:165], v193 offset:36864
	ds_read_b128 v[178:181], v193 offset:41472
	v_exp_f32_e32 v38, v38
	v_exp_f32_e32 v39, v39
	v_add_f32_e32 v247, v36, v247
	v_add_f32_e32 v247, v37, v247
	v_cvt_pk_bf16_f32 v75, v36, v37
	v_mfma_f32_32x32x16_bf16 v[2:17], v[216:219], v[66:69], v[2:17]
	ds_read_b128 v[166:169], v193 offset:36896
	ds_read_b128 v[182:185], v193 offset:41504
	v_exp_f32_e32 v40, v40
	v_exp_f32_e32 v41, v41
	v_add_f32_e32 v247, v38, v247
	v_add_f32_e32 v247, v39, v247
	v_cvt_pk_bf16_f32 v76, v38, v39
	v_mfma_f32_32x32x16_bf16 v[18:33], v[90:93], v[70:73], v[18:33]
	ds_read_b128 v[170:173], v193 offset:36928
	ds_read_b128 v[186:189], v193 offset:41536
	v_exp_f32_e32 v42, v42
	v_exp_f32_e32 v43, v43
	v_add_f32_e32 v247, v40, v247
	v_add_f32_e32 v247, v41, v247
	v_cvt_pk_bf16_f32 v77, v40, v41
	v_mfma_f32_32x32x16_bf16 v[2:17], v[220:223], v[70:73], v[2:17]
	ds_read_b128 v[174:177], v193 offset:36960
	ds_read_b128 v[82:85], v193 offset:41568
	v_exp_f32_e32 v44, v44
	v_exp_f32_e32 v45, v45
	v_add_f32_e32 v247, v42, v247
	v_add_f32_e32 v247, v43, v247
	v_cvt_pk_bf16_f32 v78, v42, v43
	v_mfma_f32_32x32x16_bf16 v[18:33], v[94:97], v[74:77], v[18:33]
	v_exp_f32_e32 v46, v46
	v_exp_f32_e32 v47, v47
	v_add_f32_e32 v247, v44, v247
	v_add_f32_e32 v247, v45, v247
	v_cvt_pk_bf16_f32 v79, v44, v45
	v_mfma_f32_32x32x16_bf16 v[2:17], v[224:227], v[74:77], v[2:17]
	v_exp_f32_e32 v48, v48
	v_exp_f32_e32 v49, v49
	v_add_f32_e32 v247, v46, v247
	v_add_f32_e32 v247, v47, v247
	v_cvt_pk_bf16_f32 v80, v46, v47
	v_cvt_pk_bf16_f32 v81, v48, v49
	v_add_f32_e32 v247, v48, v247
	v_add_f32_e32 v247, v49, v247
	v_mfma_f32_32x32x16_bf16 v[18:33], v[212:215], v[78:81], v[18:33]
	v_mfma_f32_32x32x16_bf16 v[2:17], v[242:245], v[78:81], v[2:17]
	v_add_f32_e32 v210, v210, v246
	v_add_f32_e32 v210, v210, v247
	s_waitcnt lgkmcnt(0)
	v_mfma_f32_32x32x16_bf16 v[66:81], v[162:165], v[130:133], v[50:65]
	s_min_i32 s24, s10, s58
	s_mul_i32 s44, s24, 0xa0000
	s_add_u32 s44, s3, s44
	s_addc_u32 s45, s12, 0
	s_lshl_b32 s46, s24, 7
	s_add_u32 s46, s15, s46
	s_addc_u32 s47, s23, 0
	global_load_dwordx4 v[146:149], v252, s[44:45] offset:1024
	global_load_dwordx4 v[150:153], v253, s[46:47]
	v_exp_f32_e32 v114, v114
	v_exp_f32_e32 v115, v115
	v_exp_f32_e32 v116, v116
	v_exp_f32_e32 v117, v117
	v_add_f32_e32 v246, v114, v115
	v_cvt_pk_bf16_f32 v114, v114, v115
	ds_read_b128 v[86:89], v248 offset:55296
	ds_read_b128 v[216:219], v248 offset:59904
	v_exp_f32_e32 v118, v118
	v_exp_f32_e32 v119, v119
	v_add_f32_e32 v246, v116, v246
	v_add_f32_e32 v246, v117, v246
	v_cvt_pk_bf16_f32 v115, v116, v117
	v_mfma_f32_32x32x16_bf16 v[34:49], v[178:181], v[130:133], v[50:65]
	ds_read_b128 v[90:93], v248 offset:55328
	ds_read_b128 v[220:223], v248 offset:59936
	v_exp_f32_e32 v120, v120
	v_exp_f32_e32 v121, v121
	v_add_f32_e32 v246, v118, v246
	v_add_f32_e32 v246, v119, v246
	v_cvt_pk_bf16_f32 v116, v118, v119
	v_mfma_f32_32x32x16_bf16 v[66:81], v[166:169], v[134:137], v[66:81]
	ds_read_b128 v[94:97], v248 offset:55360
	ds_read_b128 v[224:227], v248 offset:59968
	v_exp_f32_e32 v122, v122
	v_exp_f32_e32 v123, v123
	v_add_f32_e32 v246, v120, v246
	v_add_f32_e32 v246, v121, v246
	v_cvt_pk_bf16_f32 v117, v120, v121
	v_mfma_f32_32x32x16_bf16 v[34:49], v[182:185], v[134:137], v[34:49]
	ds_read_b128 v[212:215], v248 offset:55392
	ds_read_b128 v[242:245], v248 offset:60000
	v_exp_f32_e32 v124, v124
	v_exp_f32_e32 v125, v125
	v_add_f32_e32 v246, v122, v246
	v_add_f32_e32 v246, v123, v246
	v_cvt_pk_bf16_f32 v118, v122, v123
	v_mfma_f32_32x32x16_bf16 v[66:81], v[170:173], v[138:141], v[66:81]
	s_cmp_ge_u32 s11, s16
	s_cbranch_scc1 .Lattn_fx_skipw4
	s_waitcnt vmcnt(2)
	ds_write_b128 v192, v[154:157]
	ds_write_b128 v204, v[158:161] offset:9216
